# out-proj/FFN-down GEMM k-loop also uses scalar base plus 32-bit lane offsets (14 64-bit VALU address ops per k-step removed); fixed VALU->readfirstlane wait state in its preheader
# baseline (speedup 1.0000x reference)
.LBB0_909:
	s_and_b32 s2, s14, 7
	s_or_b32 s2, s2, s33
	s_lshl_b32 s15, s2, 8
	v_add_u32_e32 v0, s15, v227
	s_lshl_b32 s2, s14, 4
	v_add_u32_e32 v1, 32, v0
	s_and_b32 s16, s2, 0x380
	v_mad_i64_i32 v[204:205], s[2:3], v1, s10, 0
	v_add_u32_e32 v1, 64, v0
	v_mad_i64_i32 v[206:207], s[2:3], v1, s10, 0
	v_add_u32_e32 v1, 0x60, v0
	v_mad_i64_i32 v[208:209], s[2:3], v1, s10, 0
	v_add_u32_e32 v1, 0x80, v0
	v_mad_i64_i32 v[210:211], s[2:3], v1, s10, 0
	v_add_u32_e32 v1, 0xa0, v0
	v_mad_i64_i32 v[202:203], s[2:3], v0, s10, 0
	v_mad_i64_i32 v[212:213], s[2:3], v1, s10, 0
	v_add_u32_e32 v1, 0xc0, v0
	v_add_u32_e32 v0, 0xe0, v0
	v_mad_i64_i32 v[216:217], s[2:3], v0, s10, 0
	v_add_u32_e32 v0, s16, v227
	v_mad_i64_i32 v[214:215], s[2:3], v1, s10, 0
	v_add_u32_e32 v1, 32, v0
	v_mad_i64_i32 v[218:219], s[2:3], v0, s10, 0
	v_mad_i64_i32 v[220:221], s[2:3], v1, s10, 0
	v_add_u32_e32 v1, 64, v0
	v_add_u32_e32 v0, 0x60, v0
	v_mad_i64_i32 v[222:223], s[2:3], v1, s10, 0
	v_mad_i64_i32 v[224:225], s[2:3], v0, s10, 0
	v_lshl_add_u64 v[0:1], v[224:225], 1, v[194:195]
	v_lshl_add_u64 v[4:5], v[222:223], 1, v[194:195]
	v_lshl_add_u64 v[8:9], v[220:221], 1, v[194:195]
	v_lshl_add_u64 v[12:13], v[218:219], 1, v[194:195]
	v_lshl_add_u64 v[16:17], v[216:217], 1, v[192:193]
	v_lshl_add_u64 v[20:21], v[214:215], 1, v[192:193]
	v_lshl_add_u64 v[24:25], v[212:213], 1, v[192:193]
	v_lshl_add_u64 v[28:29], v[210:211], 1, v[192:193]
	v_lshl_add_u64 v[32:33], v[208:209], 1, v[192:193]
	v_lshl_add_u64 v[36:37], v[206:207], 1, v[192:193]
	v_lshl_add_u64 v[40:41], v[204:205], 1, v[192:193]
	v_lshl_add_u64 v[44:45], v[202:203], 1, v[192:193]
	global_load_dwordx4 v[0:3], v[0:1], off sc1
	s_nop 0
	global_load_dwordx4 v[4:7], v[4:5], off sc1
	s_nop 0
	global_load_dwordx4 v[8:11], v[8:9], off sc1
	s_nop 0
	global_load_dwordx4 v[12:15], v[12:13], off sc1
	s_nop 0
	global_load_dwordx4 v[16:19], v[16:17], off sc1
	s_nop 0
	global_load_dwordx4 v[20:23], v[20:21], off sc1
	s_nop 0
	global_load_dwordx4 v[24:27], v[24:25], off sc1
	s_nop 0
	global_load_dwordx4 v[28:31], v[28:29], off sc1
	s_nop 0
	global_load_dwordx4 v[32:35], v[32:33], off sc1
	s_nop 0
	global_load_dwordx4 v[36:39], v[36:37], off sc1
	s_nop 0
	global_load_dwordx4 v[40:43], v[40:41], off sc1
	s_nop 0
	global_load_dwordx4 v[44:47], v[44:45], off sc1
	v_mov_b32_e32 v144, 0
	s_mov_b32 s50, 64
	s_mov_b32 s2, s13
	v_mov_b32_e32 v145, v144
	v_mov_b32_e32 v146, v144
	v_mov_b32_e32 v147, v144
	v_mov_b32_e32 v148, v144
	v_mov_b32_e32 v149, v144
	v_mov_b32_e32 v150, v144
	v_mov_b32_e32 v151, v144
	v_mov_b32_e32 v152, v144
	v_mov_b32_e32 v153, v144
	v_mov_b32_e32 v154, v144
	v_mov_b32_e32 v155, v144
	v_mov_b32_e32 v156, v144
	v_mov_b32_e32 v157, v144
	v_mov_b32_e32 v158, v144
	v_mov_b32_e32 v159, v144
	v_mov_b32_e32 v116, v144
	v_mov_b32_e32 v117, v144
	v_mov_b32_e32 v118, v144
	v_mov_b32_e32 v119, v144
	v_mov_b32_e32 v128, v144
	v_mov_b32_e32 v129, v144
	v_mov_b32_e32 v130, v144
	v_mov_b32_e32 v131, v144
	v_mov_b32_e32 v136, v144
	v_mov_b32_e32 v137, v144
	v_mov_b32_e32 v138, v144
	v_mov_b32_e32 v139, v144
	v_mov_b32_e32 v140, v144
	v_mov_b32_e32 v141, v144
	v_mov_b32_e32 v142, v144
	v_mov_b32_e32 v143, v144
	v_mov_b32_e32 v100, v144
	v_mov_b32_e32 v101, v144
	v_mov_b32_e32 v102, v144
	v_mov_b32_e32 v103, v144
	v_mov_b32_e32 v112, v144
	v_mov_b32_e32 v113, v144
	v_mov_b32_e32 v114, v144
	v_mov_b32_e32 v115, v144
	v_mov_b32_e32 v124, v144
	v_mov_b32_e32 v125, v144
	v_mov_b32_e32 v126, v144
	v_mov_b32_e32 v127, v144
	v_mov_b32_e32 v132, v144
	v_mov_b32_e32 v133, v144
	v_mov_b32_e32 v134, v144
	v_mov_b32_e32 v135, v144
	v_mov_b32_e32 v88, v144
	v_mov_b32_e32 v89, v144
	v_mov_b32_e32 v90, v144
	v_mov_b32_e32 v91, v144
	v_mov_b32_e32 v96, v144
	v_mov_b32_e32 v97, v144
	v_mov_b32_e32 v98, v144
	v_mov_b32_e32 v99, v144
	v_mov_b32_e32 v108, v144
	v_mov_b32_e32 v109, v144
	v_mov_b32_e32 v110, v144
	v_mov_b32_e32 v111, v144
	v_mov_b32_e32 v120, v144
	v_mov_b32_e32 v121, v144
	v_mov_b32_e32 v122, v144
	v_mov_b32_e32 v123, v144
	v_mov_b32_e32 v80, v144
	v_mov_b32_e32 v81, v144
	v_mov_b32_e32 v82, v144
	v_mov_b32_e32 v83, v144
	v_mov_b32_e32 v84, v144
	v_mov_b32_e32 v85, v144
	v_mov_b32_e32 v86, v144
	v_mov_b32_e32 v87, v144
	v_mov_b32_e32 v92, v144
	v_mov_b32_e32 v93, v144
	v_mov_b32_e32 v94, v144
	v_mov_b32_e32 v95, v144
	v_mov_b32_e32 v104, v144
	v_mov_b32_e32 v105, v144
	v_mov_b32_e32 v106, v144
	v_mov_b32_e32 v107, v144
	v_mov_b32_e32 v48, v144
	v_mov_b32_e32 v49, v144
	v_mov_b32_e32 v50, v144
	v_mov_b32_e32 v51, v144
	v_mov_b32_e32 v52, v144
	v_mov_b32_e32 v53, v144
	v_mov_b32_e32 v54, v144
	v_mov_b32_e32 v55, v144
	v_mov_b32_e32 v56, v144
	v_mov_b32_e32 v57, v144
	v_mov_b32_e32 v58, v144
	v_mov_b32_e32 v59, v144
	v_mov_b32_e32 v72, v144
	v_mov_b32_e32 v73, v144
	v_mov_b32_e32 v74, v144
	v_mov_b32_e32 v75, v144
	v_mov_b32_e32 v76, v144
	v_mov_b32_e32 v77, v144
	v_mov_b32_e32 v78, v144
	v_mov_b32_e32 v79, v144
	v_mov_b32_e32 v68, v144
	v_mov_b32_e32 v69, v144
	v_mov_b32_e32 v70, v144
	v_mov_b32_e32 v71, v144
	v_mov_b32_e32 v64, v144
	v_mov_b32_e32 v65, v144
	v_mov_b32_e32 v66, v144
	v_mov_b32_e32 v67, v144
	v_mov_b32_e32 v60, v144
	v_mov_b32_e32 v61, v144
	v_mov_b32_e32 v62, v144
	v_mov_b32_e32 v63, v144
	v_mov_b32_e32 v160, v144
	v_mov_b32_e32 v161, v144
	v_mov_b32_e32 v162, v144
	v_mov_b32_e32 v163, v144
	v_mov_b32_e32 v164, v144
	v_mov_b32_e32 v165, v144
	v_mov_b32_e32 v166, v144
	v_mov_b32_e32 v167, v144
	v_mov_b32_e32 v168, v144
	v_mov_b32_e32 v169, v144
	v_mov_b32_e32 v170, v144
	v_mov_b32_e32 v171, v144
	v_mov_b32_e32 v172, v144
	v_mov_b32_e32 v173, v144
	v_mov_b32_e32 v174, v144
	v_mov_b32_e32 v175, v144
	v_lshl_add_u64 v[176:177], v[202:203], 1, v[192:193]
	s_nop 3
	v_readfirstlane_b32 s76, v176
	v_readfirstlane_b32 s77, v177
	s_sub_u32 s76, s76, 0x400000
	s_subb_u32 s77, s77, 0
	v_subrev_u32_e32 v202, s76, v176
	v_lshl_add_u64 v[176:177], v[204:205], 1, v[192:193]
	v_subrev_u32_e32 v204, s76, v176
	v_lshl_add_u64 v[176:177], v[206:207], 1, v[192:193]
	v_subrev_u32_e32 v206, s76, v176
	v_lshl_add_u64 v[176:177], v[208:209], 1, v[192:193]
	v_subrev_u32_e32 v208, s76, v176
	v_lshl_add_u64 v[176:177], v[210:211], 1, v[192:193]
	v_subrev_u32_e32 v210, s76, v176
	v_lshl_add_u64 v[176:177], v[212:213], 1, v[192:193]
	v_subrev_u32_e32 v212, s76, v176
	v_lshl_add_u64 v[176:177], v[214:215], 1, v[192:193]
	v_subrev_u32_e32 v214, s76, v176
	v_lshl_add_u64 v[176:177], v[216:217], 1, v[192:193]
	v_subrev_u32_e32 v216, s76, v176
	v_lshl_add_u64 v[176:177], v[218:219], 1, v[194:195]
	s_nop 3
	v_readfirstlane_b32 s78, v176
	v_readfirstlane_b32 s79, v177
	s_sub_u32 s78, s78, 0x400000
	s_subb_u32 s79, s79, 0
	v_subrev_u32_e32 v218, s78, v176
	v_lshl_add_u64 v[176:177], v[220:221], 1, v[194:195]
	v_subrev_u32_e32 v220, s78, v176
	v_lshl_add_u64 v[176:177], v[222:223], 1, v[194:195]
	v_subrev_u32_e32 v222, s78, v176
	v_lshl_add_u64 v[176:177], v[224:225], 1, v[194:195]
	v_subrev_u32_e32 v224, s78, v176
.LBB0_910:
	s_lshl_b64 s[8:9], s[50:51], 1
	s_waitcnt vmcnt(63) expcnt(7) lgkmcnt(15)
	s_barrier
	s_waitcnt vmcnt(0)
	ds_write_b128 v240, v[44:47]
	ds_write_b128 v240, v[40:43] offset:5120
	ds_write_b128 v240, v[36:39] offset:10240
	ds_write_b128 v240, v[32:35] offset:15360
	ds_write_b128 v240, v[28:31] offset:20480
	ds_write_b128 v240, v[24:27] offset:25600
	ds_write_b128 v240, v[20:23] offset:30720
	ds_write_b128 v240, v[16:19] offset:35840
	ds_write_b128 v240, v[12:15] offset:40960
	ds_write_b128 v240, v[8:11] offset:46080
	ds_write_b128 v240, v[4:7] offset:51200
	ds_write_b128 v240, v[0:3] offset:56320
	s_add_u32 s80, s76, s8
	s_addc_u32 s81, s77, s9
	s_add_u32 s82, s78, s8
	s_addc_u32 s83, s79, s9
	s_waitcnt lgkmcnt(0)
	s_barrier
	global_load_dwordx4 v[44:47], v202, s[80:81] sc1
	global_load_dwordx4 v[40:43], v204, s[80:81] sc1
	global_load_dwordx4 v[36:39], v206, s[80:81] sc1
	global_load_dwordx4 v[32:35], v208, s[80:81] sc1
	global_load_dwordx4 v[28:31], v210, s[80:81] sc1
	global_load_dwordx4 v[24:27], v212, s[80:81] sc1
	global_load_dwordx4 v[20:23], v214, s[80:81] sc1
	global_load_dwordx4 v[16:19], v216, s[80:81] sc1
	global_load_dwordx4 v[12:15], v218, s[82:83] sc1
	global_load_dwordx4 v[8:11], v220, s[82:83] sc1
	global_load_dwordx4 v[4:7], v222, s[82:83] sc1
	global_load_dwordx4 v[0:3], v224, s[82:83] sc1
	ds_read_b128 v[176:179], v241 offset:40960
	ds_read_b128 v[184:187], v241 offset:43520
	ds_read_b128 v[188:191], v241 offset:46080
	ds_read_b128 v[230:233], v241 offset:48640
	ds_read_b128 v[180:183], v239
	ds_read_b128 v[244:247], v239 offset:2560
	s_add_i32 s2, s2, -1
	s_add_i32 s50, s50, 64
	s_waitcnt lgkmcnt(1)
	v_mfma_f32_16x16x32_bf16 v[60:63], v[176:179], v[180:183], v[60:63]
	v_mfma_f32_16x16x32_bf16 v[64:67], v[184:187], v[180:183], v[64:67]
	v_mfma_f32_16x16x32_bf16 v[68:71], v[188:191], v[180:183], v[68:71]
	v_mfma_f32_16x16x32_bf16 v[76:79], v[230:233], v[180:183], v[76:79]
	ds_read_b128 v[180:183], v239 offset:5120
	s_waitcnt lgkmcnt(1)
	v_mfma_f32_16x16x32_bf16 v[72:75], v[176:179], v[244:247], v[72:75]
	v_mfma_f32_16x16x32_bf16 v[56:59], v[184:187], v[244:247], v[56:59]
	v_mfma_f32_16x16x32_bf16 v[52:55], v[188:191], v[244:247], v[52:55]
	v_mfma_f32_16x16x32_bf16 v[48:51], v[230:233], v[244:247], v[48:51]
	ds_read_b128 v[244:247], v239 offset:7680
	s_waitcnt lgkmcnt(1)
	v_mfma_f32_16x16x32_bf16 v[104:107], v[176:179], v[180:183], v[104:107]
	v_mfma_f32_16x16x32_bf16 v[92:95], v[184:187], v[180:183], v[92:95]
	v_mfma_f32_16x16x32_bf16 v[84:87], v[188:191], v[180:183], v[84:87]
	v_mfma_f32_16x16x32_bf16 v[80:83], v[230:233], v[180:183], v[80:83]
	ds_read_b128 v[180:183], v239 offset:10240
	s_waitcnt lgkmcnt(1)
	v_mfma_f32_16x16x32_bf16 v[120:123], v[176:179], v[244:247], v[120:123]
	v_mfma_f32_16x16x32_bf16 v[108:111], v[184:187], v[244:247], v[108:111]
	v_mfma_f32_16x16x32_bf16 v[96:99], v[188:191], v[244:247], v[96:99]
	v_mfma_f32_16x16x32_bf16 v[88:91], v[230:233], v[244:247], v[88:91]
	ds_read_b128 v[244:247], v239 offset:12800
	s_waitcnt lgkmcnt(1)
	v_mfma_f32_16x16x32_bf16 v[132:135], v[176:179], v[180:183], v[132:135]
	v_mfma_f32_16x16x32_bf16 v[124:127], v[184:187], v[180:183], v[124:127]
	v_mfma_f32_16x16x32_bf16 v[112:115], v[188:191], v[180:183], v[112:115]
	v_mfma_f32_16x16x32_bf16 v[100:103], v[230:233], v[180:183], v[100:103]
	ds_read_b128 v[180:183], v239 offset:15360
	s_waitcnt lgkmcnt(1)
	v_mfma_f32_16x16x32_bf16 v[140:143], v[176:179], v[244:247], v[140:143]
	v_mfma_f32_16x16x32_bf16 v[136:139], v[184:187], v[244:247], v[136:139]
	v_mfma_f32_16x16x32_bf16 v[128:131], v[188:191], v[244:247], v[128:131]
	v_mfma_f32_16x16x32_bf16 v[116:119], v[230:233], v[244:247], v[116:119]
	ds_read_b128 v[244:247], v242
	s_waitcnt lgkmcnt(1)
	v_mfma_f32_16x16x32_bf16 v[156:159], v[176:179], v[180:183], v[156:159]
	v_mfma_f32_16x16x32_bf16 v[152:155], v[184:187], v[180:183], v[152:155]
	v_mfma_f32_16x16x32_bf16 v[148:151], v[188:191], v[180:183], v[148:151]
	v_mfma_f32_16x16x32_bf16 v[144:147], v[230:233], v[180:183], v[144:147]
	ds_read_b128 v[180:183], v239 offset:64
	s_waitcnt lgkmcnt(1)
	v_mfma_f32_16x16x32_bf16 v[160:163], v[176:179], v[244:247], v[160:163]
	ds_read_b128 v[176:179], v241 offset:41024
	v_mfma_f32_16x16x32_bf16 v[164:167], v[184:187], v[244:247], v[164:167]
	ds_read_b128 v[184:187], v241 offset:43584
	v_mfma_f32_16x16x32_bf16 v[168:171], v[188:191], v[244:247], v[168:171]
	ds_read_b128 v[188:191], v241 offset:46144
	v_mfma_f32_16x16x32_bf16 v[172:175], v[230:233], v[244:247], v[172:175]
	ds_read_b128 v[230:233], v241 offset:48704
	ds_read_b128 v[244:247], v239 offset:2624
	s_waitcnt lgkmcnt(1)
	v_mfma_f32_16x16x32_bf16 v[60:63], v[176:179], v[180:183], v[60:63]
	v_mfma_f32_16x16x32_bf16 v[64:67], v[184:187], v[180:183], v[64:67]
	v_mfma_f32_16x16x32_bf16 v[68:71], v[188:191], v[180:183], v[68:71]
	v_mfma_f32_16x16x32_bf16 v[76:79], v[230:233], v[180:183], v[76:79]
	ds_read_b128 v[180:183], v239 offset:5184
	s_waitcnt lgkmcnt(1)
	v_mfma_f32_16x16x32_bf16 v[72:75], v[176:179], v[244:247], v[72:75]
	v_mfma_f32_16x16x32_bf16 v[56:59], v[184:187], v[244:247], v[56:59]
	v_mfma_f32_16x16x32_bf16 v[52:55], v[188:191], v[244:247], v[52:55]
	v_mfma_f32_16x16x32_bf16 v[48:51], v[230:233], v[244:247], v[48:51]
	ds_read_b128 v[244:247], v239 offset:7744
	s_waitcnt lgkmcnt(1)
	v_mfma_f32_16x16x32_bf16 v[104:107], v[176:179], v[180:183], v[104:107]
	v_mfma_f32_16x16x32_bf16 v[92:95], v[184:187], v[180:183], v[92:95]
	v_mfma_f32_16x16x32_bf16 v[84:87], v[188:191], v[180:183], v[84:87]
	v_mfma_f32_16x16x32_bf16 v[80:83], v[230:233], v[180:183], v[80:83]
	ds_read_b128 v[180:183], v239 offset:10304
	s_waitcnt lgkmcnt(1)
	v_mfma_f32_16x16x32_bf16 v[120:123], v[176:179], v[244:247], v[120:123]
	v_mfma_f32_16x16x32_bf16 v[108:111], v[184:187], v[244:247], v[108:111]
	v_mfma_f32_16x16x32_bf16 v[96:99], v[188:191], v[244:247], v[96:99]
	v_mfma_f32_16x16x32_bf16 v[88:91], v[230:233], v[244:247], v[88:91]
	ds_read_b128 v[244:247], v239 offset:12864
	s_waitcnt lgkmcnt(1)
	v_mfma_f32_16x16x32_bf16 v[132:135], v[176:179], v[180:183], v[132:135]
	v_mfma_f32_16x16x32_bf16 v[124:127], v[184:187], v[180:183], v[124:127]
	v_mfma_f32_16x16x32_bf16 v[112:115], v[188:191], v[180:183], v[112:115]
	v_mfma_f32_16x16x32_bf16 v[100:103], v[230:233], v[180:183], v[100:103]
	ds_read_b128 v[180:183], v239 offset:15424
	s_waitcnt lgkmcnt(1)
	v_mfma_f32_16x16x32_bf16 v[140:143], v[176:179], v[244:247], v[140:143]
	v_mfma_f32_16x16x32_bf16 v[136:139], v[184:187], v[244:247], v[136:139]
	v_mfma_f32_16x16x32_bf16 v[128:131], v[188:191], v[244:247], v[128:131]
	v_mfma_f32_16x16x32_bf16 v[116:119], v[230:233], v[244:247], v[116:119]
	ds_read_b128 v[244:247], v242 offset:64
	s_waitcnt lgkmcnt(1)
	v_mfma_f32_16x16x32_bf16 v[156:159], v[176:179], v[180:183], v[156:159]
	v_mfma_f32_16x16x32_bf16 v[152:155], v[184:187], v[180:183], v[152:155]
	v_mfma_f32_16x16x32_bf16 v[148:151], v[188:191], v[180:183], v[148:151]
	v_mfma_f32_16x16x32_bf16 v[144:147], v[230:233], v[180:183], v[144:147]
	s_waitcnt lgkmcnt(0)
	v_mfma_f32_16x16x32_bf16 v[160:163], v[176:179], v[244:247], v[160:163]
	v_mfma_f32_16x16x32_bf16 v[164:167], v[184:187], v[244:247], v[164:167]
	v_mfma_f32_16x16x32_bf16 v[168:171], v[188:191], v[244:247], v[168:171]
	v_mfma_f32_16x16x32_bf16 v[172:175], v[230:233], v[244:247], v[172:175]
	s_cmp_eq_u32 s2, 0
	s_cbranch_scc0 .LBB0_910
	s_add_i32 s2, s15, 0xffffe000
	s_ashr_i32 s2, s2, 12
	s_mulk_i32 s2, 0x1800
	s_add_i32 s8, s2, 0x1800
	s_and_b64 s[2:3], s[18:19], exec
	s_cselect_b32 s8, 0, s8
	s_ashr_i32 s9, s8, 31
	s_barrier
	s_waitcnt vmcnt(11)
	ds_write_b128 v240, v[44:47]
	s_waitcnt vmcnt(10)
	ds_write_b128 v240, v[40:43] offset:5120
	s_waitcnt vmcnt(9)
	ds_write_b128 v240, v[36:39] offset:10240
	s_waitcnt vmcnt(8)
	ds_write_b128 v240, v[32:35] offset:15360
	s_waitcnt vmcnt(7)
	ds_write_b128 v240, v[28:31] offset:20480
	s_waitcnt vmcnt(6)
	ds_write_b128 v240, v[24:27] offset:25600
	s_waitcnt vmcnt(5)
	ds_write_b128 v240, v[20:23] offset:30720
	s_waitcnt vmcnt(4)
	ds_write_b128 v240, v[16:19] offset:35840
	s_waitcnt vmcnt(3)
	ds_write_b128 v240, v[12:15] offset:40960
	s_waitcnt vmcnt(2)
	ds_write_b128 v240, v[8:11] offset:46080
	s_waitcnt vmcnt(1)
	ds_write_b128 v240, v[4:7] offset:51200
	s_waitcnt vmcnt(0)
	ds_write_b128 v240, v[0:3] offset:56320
	s_waitcnt lgkmcnt(0)
	s_barrier
	ds_read_b128 v[0:3], v241 offset:40960
	ds_read_b128 v[4:7], v241 offset:43520
	ds_read_b128 v[8:11], v241 offset:46080
	ds_read_b128 v[12:15], v241 offset:48640
	ds_read_b128 v[16:19], v239 offset:2560
	ds_read_b128 v[20:23], v239 offset:5120
	ds_read_b128 v[24:27], v239
	ds_read_b128 v[40:43], v239 offset:7680
	s_lshl_b64 s[2:3], s[8:9], 2
	s_waitcnt lgkmcnt(3)
	v_mfma_f32_16x16x32_bf16 v[44:47], v[0:3], v[16:19], v[72:75]
	s_add_u32 s2, s11, s2
	s_addc_u32 s3, s12, s3
	v_mov_b32_e32 v201, v197
	s_waitcnt lgkmcnt(1)
	v_mfma_f32_16x16x32_bf16 v[28:31], v[0:3], v[24:27], v[60:63]
	ds_read_b128 v[72:75], v239 offset:12800
	s_add_i32 s14, s14, s53
	s_cmp_gt_u32 s14, 63
	v_mfma_f32_16x16x32_bf16 v[32:35], v[4:7], v[24:27], v[64:67]
	v_mfma_f32_16x16x32_bf16 v[36:39], v[8:11], v[24:27], v[68:71]
	v_mfma_f32_16x16x32_bf16 v[24:27], v[12:15], v[24:27], v[76:79]
	v_mfma_f32_16x16x32_bf16 v[56:59], v[4:7], v[16:19], v[56:59]
	v_mfma_f32_16x16x32_bf16 v[52:55], v[8:11], v[16:19], v[52:55]
	v_mfma_f32_16x16x32_bf16 v[16:19], v[12:15], v[16:19], v[48:51]
	s_nop 2
	ds_read_b128 v[48:51], v239 offset:10240
	v_mfma_f32_16x16x32_bf16 v[60:63], v[0:3], v[20:23], v[104:107]
	v_mfma_f32_16x16x32_bf16 v[64:67], v[4:7], v[20:23], v[92:95]
	v_mfma_f32_16x16x32_bf16 v[68:71], v[8:11], v[20:23], v[84:87]
	s_nop 1
	ds_read_b128 v[92:95], v242
	v_mfma_f32_16x16x32_bf16 v[20:23], v[12:15], v[20:23], v[80:83]
	s_waitcnt lgkmcnt(3)
	v_mfma_f32_16x16x32_bf16 v[76:79], v[0:3], v[40:43], v[120:123]
	v_mfma_f32_16x16x32_bf16 v[80:83], v[4:7], v[40:43], v[108:111]
	v_mfma_f32_16x16x32_bf16 v[84:87], v[8:11], v[40:43], v[96:99]
	v_mfma_f32_16x16x32_bf16 v[40:43], v[12:15], v[40:43], v[88:91]
	s_nop 2
	ds_read_b128 v[88:91], v239 offset:15360
	s_waitcnt lgkmcnt(2)
	v_mfma_f32_16x16x32_bf16 v[176:179], v[0:3], v[48:51], v[132:135]
	v_mfma_f32_16x16x32_bf16 v[180:183], v[4:7], v[48:51], v[124:127]
	v_mfma_f32_16x16x32_bf16 v[184:187], v[8:11], v[48:51], v[112:115]
	v_mfma_f32_16x16x32_bf16 v[48:51], v[12:15], v[48:51], v[100:103]
	v_mfma_f32_16x16x32_bf16 v[188:191], v[0:3], v[72:75], v[140:143]
	v_mfma_f32_16x16x32_bf16 v[202:205], v[4:7], v[72:75], v[136:139]
	v_mfma_f32_16x16x32_bf16 v[206:209], v[8:11], v[72:75], v[128:131]
	v_mfma_f32_16x16x32_bf16 v[210:213], v[12:15], v[72:75], v[116:119]
	s_waitcnt lgkmcnt(0)
	v_mfma_f32_16x16x32_bf16 v[156:159], v[0:3], v[88:91], v[156:159]
	v_mfma_f32_16x16x32_bf16 v[152:155], v[4:7], v[88:91], v[152:155]
	v_mfma_f32_16x16x32_bf16 v[148:151], v[8:11], v[88:91], v[148:151]
	v_mfma_f32_16x16x32_bf16 v[144:147], v[12:15], v[88:91], v[144:147]
	v_mfma_f32_16x16x32_bf16 v[0:3], v[0:3], v[92:95], v[160:163]
	v_mfma_f32_16x16x32_bf16 v[4:7], v[4:7], v[92:95], v[164:167]
	v_mfma_f32_16x16x32_bf16 v[8:11], v[8:11], v[92:95], v[168:171]
	v_mfma_f32_16x16x32_bf16 v[160:163], v[12:15], v[92:95], v[172:175]
	ds_read_b128 v[12:15], v241 offset:41024
	ds_read_b128 v[164:167], v241 offset:43584
	ds_read_b128 v[168:171], v241 offset:46144
	ds_read_b128 v[172:175], v241 offset:48704
	ds_read_b128 v[72:75], v239 offset:2624
	ds_read_b128 v[88:91], v239 offset:5184
	ds_read_b128 v[92:95], v239 offset:64
	s_waitcnt lgkmcnt(0)
	v_mfma_f32_16x16x32_bf16 v[128:131], v[172:175], v[92:95], v[24:27]
	s_nop 2
	ds_read_b128 v[24:27], v239 offset:7744
	v_mfma_f32_16x16x32_bf16 v[116:119], v[168:171], v[72:75], v[52:55]
	v_mfma_f32_16x16x32_bf16 v[112:115], v[172:175], v[72:75], v[16:19]
	s_nop 1
	ds_read_b128 v[52:55], v239 offset:15424
	ds_read_b128 v[16:19], v239 offset:10304
	v_mfma_f32_16x16x32_bf16 v[108:111], v[12:15], v[88:91], v[60:63]
	v_mfma_f32_16x16x32_bf16 v[96:99], v[172:175], v[88:91], v[20:23]
	s_nop 1
	ds_read_b128 v[60:63], v242 offset:64
	ds_read_b128 v[20:23], v239 offset:12864
	v_mfma_f32_16x16x32_bf16 v[140:143], v[12:15], v[92:95], v[28:31]
	v_mfma_f32_16x16x32_bf16 v[136:139], v[164:167], v[92:95], v[32:35]
	v_mfma_f32_16x16x32_bf16 v[132:135], v[168:171], v[92:95], v[36:39]
	v_mfma_f32_16x16x32_bf16 v[124:127], v[12:15], v[72:75], v[44:47]
	v_mfma_f32_16x16x32_bf16 v[120:123], v[164:167], v[72:75], v[56:59]
	v_mfma_f32_16x16x32_bf16 v[104:107], v[164:167], v[88:91], v[64:67]
	v_mfma_f32_16x16x32_bf16 v[100:103], v[168:171], v[88:91], v[68:71]
	s_waitcnt lgkmcnt(4)
	v_mfma_f32_16x16x32_bf16 v[92:95], v[12:15], v[24:27], v[76:79]
	v_mfma_f32_16x16x32_bf16 v[88:91], v[164:167], v[24:27], v[80:83]
	v_mfma_f32_16x16x32_bf16 v[80:83], v[172:175], v[24:27], v[40:43]
	s_waitcnt lgkmcnt(2)
	v_mfma_f32_16x16x32_bf16 v[76:79], v[12:15], v[16:19], v[176:179]
	v_mfma_f32_16x16x32_bf16 v[72:75], v[164:167], v[16:19], v[180:183]
	v_mfma_f32_16x16x32_bf16 v[64:67], v[168:171], v[16:19], v[184:187]
	v_mfma_f32_16x16x32_bf16 v[56:59], v[172:175], v[16:19], v[48:51]
	s_waitcnt lgkmcnt(0)
	v_mfma_f32_16x16x32_bf16 v[48:51], v[12:15], v[20:23], v[188:191]
	v_mfma_f32_16x16x32_bf16 v[44:47], v[164:167], v[20:23], v[202:205]
	v_mfma_f32_16x16x32_bf16 v[40:43], v[168:171], v[20:23], v[206:209]
	v_mfma_f32_16x16x32_bf16 v[36:39], v[172:175], v[20:23], v[210:213]
	v_mfma_f32_16x16x32_bf16 v[32:35], v[12:15], v[52:55], v[156:159]
	v_mfma_f32_16x16x32_bf16 v[20:23], v[172:175], v[52:55], v[144:147]
	v_mfma_f32_16x16x32_bf16 v[16:19], v[12:15], v[60:63], v[0:3]
	s_nop 1
	v_add_u32_e32 v146, s15, v238
	v_ashrrev_i32_e32 v147, 31, v146
	v_mfma_f32_16x16x32_bf16 v[12:15], v[164:167], v[60:63], v[4:7]
	s_nop 2
	v_or_b32_e32 v4, s16, v226
	v_lshlrev_b32_e32 v196, 2, v4
	v_mfma_f32_16x16x32_bf16 v[84:87], v[168:171], v[24:27], v[84:87]
	v_lshl_add_u64 v[4:5], s[2:3], 0, v[196:197]
	v_lshl_add_u64 v[144:145], v[198:199], 0, v[196:197]
	v_lshl_add_u64 v[4:5], v[4:5], 0, v[200:201]
	v_mfma_f32_16x16x32_bf16 v[24:27], v[168:171], v[52:55], v[148:151]
	s_nop 2
	v_lshlrev_b64 v[148:149], 12, v[146:147]
	v_mfma_f32_16x16x32_bf16 v[28:31], v[164:167], v[52:55], v[152:155]
	s_nop 2
	v_lshl_add_u64 v[152:153], v[144:145], 0, v[148:149]
	v_mfma_f32_16x16x32_bf16 v[8:11], v[168:171], v[60:63], v[8:11]
	v_mfma_f32_16x16x32_bf16 v[0:3], v[172:175], v[60:63], v[160:163]
	global_load_dwordx4 v[68:71], v[4:5], off sc1
	global_load_dwordx4 v[60:63], v[4:5], off offset:64 sc1
	global_load_dwordx4 v[52:55], v[4:5], off offset:128 sc1
	s_nop 0
	global_load_dwordx4 v[4:7], v[4:5], off offset:192 sc1
	s_nop 0
	global_load_dwordx4 v[148:151], v[152:153], off sc1
	s_waitcnt vmcnt(0)
	v_pk_fma_f32 v[142:143], v[142:143], v[70:71], v[150:151]
	v_pk_fma_f32 v[140:141], v[140:141], v[68:69], v[148:149]
	global_store_dwordx4 v[152:153], v[140:143], off
	global_load_dwordx4 v[140:143], v[152:153], off offset:64 sc1
	s_waitcnt vmcnt(0)
	v_pk_fma_f32 v[138:139], v[138:139], v[62:63], v[142:143]
	v_pk_fma_f32 v[136:137], v[136:137], v[60:61], v[140:141]
	global_store_dwordx4 v[152:153], v[136:139], off offset:64
	global_load_dwordx4 v[136:139], v[152:153], off offset:128 sc1
	s_waitcnt vmcnt(0)
	v_pk_fma_f32 v[134:135], v[134:135], v[54:55], v[138:139]
	v_pk_fma_f32 v[132:133], v[132:133], v[52:53], v[136:137]
	global_store_dwordx4 v[152:153], v[132:135], off offset:128
	global_load_dwordx4 v[132:135], v[152:153], off offset:192 sc1
	s_waitcnt vmcnt(0)
	v_pk_fma_f32 v[130:131], v[130:131], v[6:7], v[134:135]
	v_pk_fma_f32 v[128:129], v[128:129], v[4:5], v[132:133]
	global_store_dwordx4 v[152:153], v[128:131], off offset:192
	s_nop 1
	v_or_b32_e32 v128, 16, v146
	v_ashrrev_i32_e32 v129, 31, v128
	v_lshlrev_b64 v[128:129], 12, v[128:129]
	v_lshl_add_u64 v[132:133], v[144:145], 0, v[128:129]
	global_load_dwordx4 v[128:131], v[132:133], off sc1
	s_waitcnt vmcnt(0)
	v_pk_fma_f32 v[126:127], v[126:127], v[70:71], v[130:131]
	v_pk_fma_f32 v[124:125], v[124:125], v[68:69], v[128:129]
	global_store_dwordx4 v[132:133], v[124:127], off
	global_load_dwordx4 v[124:127], v[132:133], off offset:64 sc1
	s_waitcnt vmcnt(0)
	v_pk_fma_f32 v[122:123], v[122:123], v[62:63], v[126:127]
	v_pk_fma_f32 v[120:121], v[120:121], v[60:61], v[124:125]
	global_store_dwordx4 v[132:133], v[120:123], off offset:64
	global_load_dwordx4 v[120:123], v[132:133], off offset:128 sc1
	s_waitcnt vmcnt(0)
	v_pk_fma_f32 v[118:119], v[118:119], v[54:55], v[122:123]
	v_pk_fma_f32 v[116:117], v[116:117], v[52:53], v[120:121]
	global_store_dwordx4 v[132:133], v[116:119], off offset:128
	global_load_dwordx4 v[116:119], v[132:133], off offset:192 sc1
	s_waitcnt vmcnt(0)
	v_pk_fma_f32 v[114:115], v[114:115], v[6:7], v[118:119]
	v_pk_fma_f32 v[112:113], v[112:113], v[4:5], v[116:117]
	global_store_dwordx4 v[132:133], v[112:115], off offset:192
	s_nop 1
	v_or_b32_e32 v112, 32, v146
	v_ashrrev_i32_e32 v113, 31, v112
	v_lshlrev_b64 v[112:113], 12, v[112:113]
	v_lshl_add_u64 v[116:117], v[144:145], 0, v[112:113]
	global_load_dwordx4 v[112:115], v[116:117], off sc1
	s_waitcnt vmcnt(0)
	v_pk_fma_f32 v[110:111], v[110:111], v[70:71], v[114:115]
	v_pk_fma_f32 v[108:109], v[108:109], v[68:69], v[112:113]
	global_store_dwordx4 v[116:117], v[108:111], off
	global_load_dwordx4 v[108:111], v[116:117], off offset:64 sc1
	s_waitcnt vmcnt(0)
	v_pk_fma_f32 v[106:107], v[106:107], v[62:63], v[110:111]
	v_pk_fma_f32 v[104:105], v[104:105], v[60:61], v[108:109]
	global_store_dwordx4 v[116:117], v[104:107], off offset:64
	global_load_dwordx4 v[104:107], v[116:117], off offset:128 sc1
	s_waitcnt vmcnt(0)
	v_pk_fma_f32 v[102:103], v[102:103], v[54:55], v[106:107]
	v_pk_fma_f32 v[100:101], v[100:101], v[52:53], v[104:105]
	global_store_dwordx4 v[116:117], v[100:103], off offset:128
	global_load_dwordx4 v[100:103], v[116:117], off offset:192 sc1
	s_waitcnt vmcnt(0)
	v_pk_fma_f32 v[98:99], v[98:99], v[6:7], v[102:103]
	v_pk_fma_f32 v[96:97], v[96:97], v[4:5], v[100:101]
	global_store_dwordx4 v[116:117], v[96:99], off offset:192
	s_nop 1
	v_or_b32_e32 v96, 48, v146
	v_ashrrev_i32_e32 v97, 31, v96
	v_lshlrev_b64 v[96:97], 12, v[96:97]
	v_lshl_add_u64 v[100:101], v[144:145], 0, v[96:97]
	global_load_dwordx4 v[96:99], v[100:101], off sc1
	s_waitcnt vmcnt(0)
	v_pk_fma_f32 v[94:95], v[94:95], v[70:71], v[98:99]
	v_pk_fma_f32 v[92:93], v[92:93], v[68:69], v[96:97]
	global_store_dwordx4 v[100:101], v[92:95], off
	global_load_dwordx4 v[92:95], v[100:101], off offset:64 sc1
	s_waitcnt vmcnt(0)
	v_pk_fma_f32 v[90:91], v[90:91], v[62:63], v[94:95]
	v_pk_fma_f32 v[88:89], v[88:89], v[60:61], v[92:93]
	global_store_dwordx4 v[100:101], v[88:91], off offset:64
	global_load_dwordx4 v[88:91], v[100:101], off offset:128 sc1
	s_waitcnt vmcnt(0)
	v_pk_fma_f32 v[86:87], v[86:87], v[54:55], v[90:91]
	v_pk_fma_f32 v[84:85], v[84:85], v[52:53], v[88:89]
	global_store_dwordx4 v[100:101], v[84:87], off offset:128
	global_load_dwordx4 v[84:87], v[100:101], off offset:192 sc1
	s_waitcnt vmcnt(0)
	v_pk_fma_f32 v[82:83], v[82:83], v[6:7], v[86:87]
	v_pk_fma_f32 v[80:81], v[80:81], v[4:5], v[84:85]
	global_store_dwordx4 v[100:101], v[80:83], off offset:192
	s_nop 1
	v_or_b32_e32 v80, 64, v146
	v_ashrrev_i32_e32 v81, 31, v80
	v_lshlrev_b64 v[80:81], 12, v[80:81]
	v_lshl_add_u64 v[84:85], v[144:145], 0, v[80:81]
	global_load_dwordx4 v[80:83], v[84:85], off sc1
	s_waitcnt vmcnt(0)
	v_pk_fma_f32 v[78:79], v[78:79], v[70:71], v[82:83]
	v_pk_fma_f32 v[76:77], v[76:77], v[68:69], v[80:81]
	global_store_dwordx4 v[84:85], v[76:79], off
	global_load_dwordx4 v[76:79], v[84:85], off offset:64 sc1
	s_waitcnt vmcnt(0)
	v_pk_fma_f32 v[74:75], v[74:75], v[62:63], v[78:79]
	v_pk_fma_f32 v[72:73], v[72:73], v[60:61], v[76:77]
	global_store_dwordx4 v[84:85], v[72:75], off offset:64
	global_load_dwordx4 v[72:75], v[84:85], off offset:128 sc1
	s_waitcnt vmcnt(0)
	v_pk_fma_f32 v[66:67], v[66:67], v[54:55], v[74:75]
	v_pk_fma_f32 v[64:65], v[64:65], v[52:53], v[72:73]
	global_store_dwordx4 v[84:85], v[64:67], off offset:128
	global_load_dwordx4 v[64:67], v[84:85], off offset:192 sc1
	s_waitcnt vmcnt(0)
	v_pk_fma_f32 v[58:59], v[58:59], v[6:7], v[66:67]
	v_pk_fma_f32 v[56:57], v[56:57], v[4:5], v[64:65]
	global_store_dwordx4 v[84:85], v[56:59], off offset:192
	s_nop 1
	v_or_b32_e32 v56, 0x50, v146
	v_ashrrev_i32_e32 v57, 31, v56
	v_lshlrev_b64 v[56:57], 12, v[56:57]
	v_lshl_add_u64 v[64:65], v[144:145], 0, v[56:57]
	global_load_dwordx4 v[56:59], v[64:65], off sc1
	s_waitcnt vmcnt(0)
	v_pk_fma_f32 v[50:51], v[50:51], v[70:71], v[58:59]
	v_pk_fma_f32 v[48:49], v[48:49], v[68:69], v[56:57]
	global_store_dwordx4 v[64:65], v[48:51], off
	global_load_dwordx4 v[48:51], v[64:65], off offset:64 sc1
	s_waitcnt vmcnt(0)
	v_pk_fma_f32 v[46:47], v[46:47], v[62:63], v[50:51]
	v_pk_fma_f32 v[44:45], v[44:45], v[60:61], v[48:49]
	global_store_dwordx4 v[64:65], v[44:47], off offset:64
	global_load_dwordx4 v[44:47], v[64:65], off offset:128 sc1
	s_waitcnt vmcnt(0)
	v_pk_fma_f32 v[42:43], v[42:43], v[54:55], v[46:47]
	v_pk_fma_f32 v[40:41], v[40:41], v[52:53], v[44:45]
	global_store_dwordx4 v[64:65], v[40:43], off offset:128
	global_load_dwordx4 v[40:43], v[64:65], off offset:192 sc1
	s_waitcnt vmcnt(0)
	v_pk_fma_f32 v[38:39], v[38:39], v[6:7], v[42:43]
	v_pk_fma_f32 v[36:37], v[36:37], v[4:5], v[40:41]
	global_store_dwordx4 v[64:65], v[36:39], off offset:192
	s_nop 1
	v_or_b32_e32 v36, 0x60, v146
	v_ashrrev_i32_e32 v37, 31, v36
	v_lshlrev_b64 v[36:37], 12, v[36:37]
	v_lshl_add_u64 v[40:41], v[144:145], 0, v[36:37]
	global_load_dwordx4 v[36:39], v[40:41], off sc1
	s_waitcnt vmcnt(0)
	v_pk_fma_f32 v[34:35], v[34:35], v[70:71], v[38:39]
	v_pk_fma_f32 v[32:33], v[32:33], v[68:69], v[36:37]
	global_store_dwordx4 v[40:41], v[32:35], off
	global_load_dwordx4 v[32:35], v[40:41], off offset:64 sc1
	s_waitcnt vmcnt(0)
	v_pk_fma_f32 v[30:31], v[30:31], v[62:63], v[34:35]
	v_pk_fma_f32 v[28:29], v[28:29], v[60:61], v[32:33]
	global_store_dwordx4 v[40:41], v[28:31], off offset:64
	global_load_dwordx4 v[28:31], v[40:41], off offset:128 sc1
	s_waitcnt vmcnt(0)
	v_pk_fma_f32 v[26:27], v[26:27], v[54:55], v[30:31]
	v_pk_fma_f32 v[24:25], v[24:25], v[52:53], v[28:29]
	global_store_dwordx4 v[40:41], v[24:27], off offset:128
	global_load_dwordx4 v[24:27], v[40:41], off offset:192 sc1
	s_waitcnt vmcnt(0)
	v_pk_fma_f32 v[22:23], v[22:23], v[6:7], v[26:27]
	v_pk_fma_f32 v[20:21], v[20:21], v[4:5], v[24:25]
	global_store_dwordx4 v[40:41], v[20:23], off offset:192
	s_nop 1
	v_or_b32_e32 v20, 0x70, v146
	v_ashrrev_i32_e32 v21, 31, v20
	v_lshlrev_b64 v[20:21], 12, v[20:21]
	v_lshl_add_u64 v[20:21], v[144:145], 0, v[20:21]
	global_load_dwordx4 v[22:25], v[20:21], off sc1
	s_waitcnt vmcnt(0)
	v_pk_fma_f32 v[18:19], v[18:19], v[70:71], v[24:25]
	v_pk_fma_f32 v[16:17], v[16:17], v[68:69], v[22:23]
	global_store_dwordx4 v[20:21], v[16:19], off
	global_load_dwordx4 v[16:19], v[20:21], off offset:64 sc1
	s_waitcnt vmcnt(0)
	v_pk_fma_f32 v[14:15], v[14:15], v[62:63], v[18:19]
	v_pk_fma_f32 v[12:13], v[12:13], v[60:61], v[16:17]
	global_store_dwordx4 v[20:21], v[12:15], off offset:64
	global_load_dwordx4 v[12:15], v[20:21], off offset:128 sc1
	s_waitcnt vmcnt(0)
	v_pk_fma_f32 v[10:11], v[10:11], v[54:55], v[14:15]
	v_pk_fma_f32 v[8:9], v[8:9], v[52:53], v[12:13]
	global_store_dwordx4 v[20:21], v[8:11], off offset:128
	global_load_dwordx4 v[8:11], v[20:21], off offset:192 sc1
	s_waitcnt vmcnt(0)
	v_pk_fma_f32 v[2:3], v[2:3], v[6:7], v[10:11]
	v_pk_fma_f32 v[0:1], v[0:1], v[4:5], v[8:9]
	global_store_dwordx4 v[20:21], v[0:3], off offset:192
	s_cbranch_scc0 .LBB0_909
